# attention-A: next-tile global loads and loop bookkeeping issued ahead of the per-step barrier (in the staging-write drain shadow)
# speedup vs baseline: 1.0061x; 1.0006x over previous
; __device__ __forceinline__ void lds_barrier() { asm volatile("s_waitcnt lgkmcnt(0)" ::: "memory"); __builtin_amdgcn_s_barrier(); asm volatile("" ::: "memory"); }
; #define ATT_GLOAD(j) do { _Pragma("unroll") for (int _i = 0; _i < 2; ++_i) { const size_t _o = (size_t)((j) * 64 + srow + 32 * _i) * 1024 + sch * 8; \
;         kr[_i] = *(const GAS u32x4*)(Kp + _o); vr[_i] = *(const GAS u32x4*)(Vp + _o); } } while (0)
; template <int MODE>
; __device__ void attn_block(LAS unsigned char* lds, const bf16_t* Qp, const bf16_t* Kp, const bf16_t* Vp, int qb, const unsigned* maskp, const bf16_t* sga, bf16_t* outp, const float negMB) {
;     ...
;     for (int j = 0; j < nt; ++j) {
;         lds_barrier();
;         const int sn = (sj == 2) ? 0 : sj + 1;
;         if (j + 1 < nt) ATT_GLOAD(j + 1);
.LBB0_859:
	s_add_i32 s8, s57, 0x101
	s_cmp_lt_i32 s8, s53
	s_mov_b32 s58, s34
	s_cselect_b64 s[30:31], -1, 0
	s_cmp_ge_i32 s8, s53
	s_cbranch_scc1 .LBB0_861
	global_load_dwordx4 v[148:151], v240, s[100:101]
	global_load_dwordx4 v[152:155], v241, s[100:101]
	global_load_dwordx4 v[160:163], v242, s[100:101]
	global_load_dwordx4 v[164:167], v243, s[100:101]
	s_add_u32 s100, s100, 0x20000
	s_addc_u32 s101, s101, 0
.LBB0_861:
	s_waitcnt lgkmcnt(0)
	s_barrier
	s_add_i32 s59, s57, 0x100
	s_bitcmp1_b32 s59, 0
	s_cselect_b64 s[62:63], -1, 0
	s_mov_b64 s[34:35], -1
	s_and_b64 vcc, exec, s[62:63]
	s_cbranch_vccz .LBB0_863
	s_mov_b64 s[34:35], 0
	v_mov_b32_e32 v176, v159
	v_mov_b32_e32 v177, v158
